# v126 plus L2 prefetch (dummy 4-byte loads) of the residual tile lines at the head of the P2 and P8 epilogue ladders
# baseline (speedup 1.0000x reference)
.LBB0_475:
	v_lshl_add_u32 v132, s27, 8, v1
	v_ashrrev_i32_e32 v133, 31, v132
	v_lshl_or_b32 v130, s10, 8, v215
	v_lshlrev_b64 v[134:135], 11, v[132:133]
	v_ashrrev_i32_e32 v131, 31, v130
	v_lshl_add_u64 v[134:135], s[88:89], 0, v[134:135]
	v_lshl_add_u64 v[134:135], v[130:131], 1, v[134:135]
	global_load_dwordx2 v[136:137], v[134:135], off
	global_load_dwordx2 v[140:141], v[134:135], off offset:32
	global_load_dwordx2 v[144:145], v[134:135], off offset:256
	global_load_dwordx2 v[148:149], v[134:135], off offset:288
	v_add_co_u32_e32 v138, vcc, 0x8000, v134
	s_nop 1
	v_addc_co_u32_e32 v139, vcc, 0, v135, vcc
	global_load_dword v142, v[138:139], off
	global_load_dword v142, v[138:139], off offset:256
	v_add_co_u32_e32 v138, vcc, 0x10000, v134
	s_nop 1
	v_addc_co_u32_e32 v139, vcc, 0, v135, vcc
	global_load_dword v142, v[138:139], off
	global_load_dword v142, v[138:139], off offset:256
	v_add_co_u32_e32 v138, vcc, 0x18000, v134
	s_nop 1
	v_addc_co_u32_e32 v139, vcc, 0, v135, vcc
	global_load_dword v142, v[138:139], off
	global_load_dword v142, v[138:139], off offset:256
	v_add_co_u32_e32 v138, vcc, 0x40000, v134
	s_nop 1
	v_addc_co_u32_e32 v139, vcc, 0, v135, vcc
	global_load_dword v142, v[138:139], off
	global_load_dword v142, v[138:139], off offset:256
	v_add_co_u32_e32 v138, vcc, 0x48000, v134
	s_nop 1
	v_addc_co_u32_e32 v139, vcc, 0, v135, vcc
	global_load_dword v142, v[138:139], off
	global_load_dword v142, v[138:139], off offset:256
	v_add_co_u32_e32 v138, vcc, 0x50000, v134
	s_nop 1
	v_addc_co_u32_e32 v139, vcc, 0, v135, vcc
	global_load_dword v142, v[138:139], off
	global_load_dword v142, v[138:139], off offset:256
	v_add_co_u32_e32 v138, vcc, 0x58000, v134
	s_nop 1
	v_addc_co_u32_e32 v139, vcc, 0, v135, vcc
	global_load_dword v142, v[138:139], off
	global_load_dword v142, v[138:139], off offset:256
	s_lshl_b32 s8, s10, 2
	s_ashr_i32 s9, s8, 31
	s_waitcnt vmcnt(0)
	v_lshlrev_b32_e32 v138, 16, v136
	v_and_b32_e32 v139, 0xffff0000, v136
	v_lshlrev_b32_e32 v136, 16, v137
	v_and_b32_e32 v137, 0xffff0000, v137
	v_pk_fma_f32 v[126:127], v[126:127], 0.5, v[138:139] op_sel_hi:[1,0,1]
	v_pk_fma_f32 v[128:129], v[128:129], 0.5, v[136:137] op_sel_hi:[1,0,1]
	v_cvt_pk_bf16_f32 v136, v126, v127
	v_mul_f32_e32 v127, v127, v127
	v_lshlrev_b32_e32 v142, 16, v140
	v_and_b32_e32 v143, 0xffff0000, v140
	v_fmac_f32_e32 v127, v126, v126
	v_mul_f32_e32 v126, v129, v129
	v_lshlrev_b32_e32 v140, 16, v141
	v_and_b32_e32 v141, 0xffff0000, v141
	v_fmac_f32_e32 v126, v128, v128
	v_pk_fma_f32 v[118:119], v[118:119], 0.5, v[142:143] op_sel_hi:[1,0,1]
	v_cvt_pk_bf16_f32 v137, v128, v129
	v_add_f32_e32 v128, v127, v126
	v_pk_fma_f32 v[120:121], v[120:121], 0.5, v[140:141] op_sel_hi:[1,0,1]
	v_cvt_pk_bf16_f32 v126, v118, v119
	v_mul_f32_e32 v119, v119, v119
	v_fmac_f32_e32 v119, v118, v118
	v_mul_f32_e32 v118, v121, v121
	v_fmac_f32_e32 v118, v120, v120
	v_lshlrev_b32_e32 v146, 16, v144
	v_and_b32_e32 v147, 0xffff0000, v144
	v_lshlrev_b32_e32 v144, 16, v145
	v_and_b32_e32 v145, 0xffff0000, v145
	v_cvt_pk_bf16_f32 v127, v120, v121
	v_add_f32_e32 v118, v119, v118
	global_store_dwordx2 v[134:135], v[126:127], off offset:32
	v_add_f32_e32 v126, v128, v118
	v_pk_fma_f32 v[118:119], v[124:125], 0.5, v[144:145] op_sel_hi:[1,0,1]
	v_pk_fma_f32 v[120:121], v[122:123], 0.5, v[146:147] op_sel_hi:[1,0,1]
	v_cvt_pk_bf16_f32 v123, v118, v119
	v_cvt_pk_bf16_f32 v122, v120, v121
	v_mul_f32_e32 v121, v121, v121
	v_mul_f32_e32 v119, v119, v119
	v_lshlrev_b32_e32 v150, 16, v148
	v_and_b32_e32 v151, 0xffff0000, v148
	v_fmac_f32_e32 v121, v120, v120
	v_fmac_f32_e32 v119, v118, v118
	v_lshlrev_b32_e32 v148, 16, v149
	v_and_b32_e32 v149, 0xffff0000, v149
	v_add_f32_e32 v118, v121, v119
	v_pk_fma_f32 v[114:115], v[114:115], 0.5, v[150:151] op_sel_hi:[1,0,1]
	v_add_f32_e32 v120, v126, v118
	v_pk_fma_f32 v[116:117], v[116:117], 0.5, v[148:149] op_sel_hi:[1,0,1]
	v_cvt_pk_bf16_f32 v118, v114, v115
	v_mul_f32_e32 v115, v115, v115
	v_fmac_f32_e32 v115, v114, v114
	v_mul_f32_e32 v114, v117, v117
	v_cvt_pk_bf16_f32 v119, v116, v117
	v_fmac_f32_e32 v114, v116, v116
	v_and_b32_e32 v116, 64, v220
	v_add_f32_e32 v114, v115, v114
	v_xor_b32_e32 v115, 16, v220
	v_add_u32_e32 v117, 64, v116
	v_cmp_lt_i32_e32 vcc, v115, v117
	v_add_f32_e32 v114, v120, v114
	global_store_dwordx2 v[134:135], v[136:137], off
	v_cndmask_b32_e32 v115, v220, v115, vcc
	v_lshlrev_b32_e32 v116, 2, v115
	ds_bpermute_b32 v115, v116, v114
	global_store_dwordx2 v[134:135], v[122:123], off offset:256
	global_store_dwordx2 v[134:135], v[118:119], off offset:288
	s_waitcnt lgkmcnt(0)
	v_add_f32_e32 v114, v114, v115
	v_xor_b32_e32 v115, 32, v220
	v_cmp_lt_i32_e32 vcc, v115, v117
	s_nop 1
	v_cndmask_b32_e32 v115, v220, v115, vcc
	v_lshlrev_b32_e32 v117, 2, v115
	ds_bpermute_b32 v115, v117, v114
	s_and_saveexec_b64 s[42:43], s[4:5]
	s_cbranch_execz .LBB0_477
	v_lshlrev_b64 v[118:119], 6, v[132:133]
	v_lshl_add_u64 v[118:119], s[0:1], 0, v[118:119]
	v_lshl_add_u64 v[118:119], s[8:9], 2, v[118:119]
	s_lshl_b32 s10, s70, 2
	v_lshl_add_u64 v[118:119], v[118:119], 0, s[10:11]
	s_waitcnt lgkmcnt(0)
	v_add_f32_e32 v114, v114, v115
	global_store_dword v[118:119], v114, off

.LBB0_1774:
	v_lshl_add_u32 v132, s48, 8, v1
	v_ashrrev_i32_e32 v133, 31, v132
	v_lshl_or_b32 v130, s18, 8, v215
	v_lshlrev_b64 v[134:135], 11, v[132:133]
	v_ashrrev_i32_e32 v131, 31, v130
	v_lshl_add_u64 v[134:135], s[88:89], 0, v[134:135]
	v_lshl_add_u64 v[134:135], v[130:131], 1, v[134:135]
	global_load_dwordx2 v[136:137], v[134:135], off
	global_load_dwordx2 v[140:141], v[134:135], off offset:32
	global_load_dwordx2 v[144:145], v[134:135], off offset:256
	global_load_dwordx2 v[148:149], v[134:135], off offset:288
	v_add_co_u32_e32 v138, vcc, 0x8000, v134
	s_nop 1
	v_addc_co_u32_e32 v139, vcc, 0, v135, vcc
	global_load_dword v142, v[138:139], off
	global_load_dword v142, v[138:139], off offset:256
	v_add_co_u32_e32 v138, vcc, 0x10000, v134
	s_nop 1
	v_addc_co_u32_e32 v139, vcc, 0, v135, vcc
	global_load_dword v142, v[138:139], off
	global_load_dword v142, v[138:139], off offset:256
	v_add_co_u32_e32 v138, vcc, 0x18000, v134
	s_nop 1
	v_addc_co_u32_e32 v139, vcc, 0, v135, vcc
	global_load_dword v142, v[138:139], off
	global_load_dword v142, v[138:139], off offset:256
	v_add_co_u32_e32 v138, vcc, 0x40000, v134
	s_nop 1
	v_addc_co_u32_e32 v139, vcc, 0, v135, vcc
	global_load_dword v142, v[138:139], off
	global_load_dword v142, v[138:139], off offset:256
	v_add_co_u32_e32 v138, vcc, 0x48000, v134
	s_nop 1
	v_addc_co_u32_e32 v139, vcc, 0, v135, vcc
	global_load_dword v142, v[138:139], off
	global_load_dword v142, v[138:139], off offset:256
	v_add_co_u32_e32 v138, vcc, 0x50000, v134
	s_nop 1
	v_addc_co_u32_e32 v139, vcc, 0, v135, vcc
	global_load_dword v142, v[138:139], off
	global_load_dword v142, v[138:139], off offset:256
	v_add_co_u32_e32 v138, vcc, 0x58000, v134
	s_nop 1
	v_addc_co_u32_e32 v139, vcc, 0, v135, vcc
	global_load_dword v142, v[138:139], off
	global_load_dword v142, v[138:139], off offset:256
	s_lshl_b32 s48, s18, 2
	s_ashr_i32 s49, s48, 31
	s_waitcnt vmcnt(0)
	v_lshlrev_b32_e32 v138, 16, v136
	v_and_b32_e32 v139, 0xffff0000, v136
	v_lshlrev_b32_e32 v136, 16, v137
	v_and_b32_e32 v137, 0xffff0000, v137
	v_pk_add_f32 v[126:127], v[126:127], v[138:139]
	v_pk_add_f32 v[128:129], v[128:129], v[136:137]
	v_cvt_pk_bf16_f32 v136, v126, v127
	v_mul_f32_e32 v127, v127, v127
	v_lshlrev_b32_e32 v142, 16, v140
	v_and_b32_e32 v143, 0xffff0000, v140
	v_fmac_f32_e32 v127, v126, v126
	v_mul_f32_e32 v126, v129, v129
	v_lshlrev_b32_e32 v140, 16, v141
	v_and_b32_e32 v141, 0xffff0000, v141
	v_fmac_f32_e32 v126, v128, v128
	v_pk_add_f32 v[118:119], v[118:119], v[142:143]
	v_cvt_pk_bf16_f32 v137, v128, v129
	v_add_f32_e32 v128, v127, v126
	v_pk_add_f32 v[120:121], v[120:121], v[140:141]
	v_cvt_pk_bf16_f32 v126, v118, v119
	v_mul_f32_e32 v119, v119, v119
	v_fmac_f32_e32 v119, v118, v118
	v_mul_f32_e32 v118, v121, v121
	v_fmac_f32_e32 v118, v120, v120
	v_lshlrev_b32_e32 v146, 16, v144
	v_and_b32_e32 v147, 0xffff0000, v144
	v_lshlrev_b32_e32 v144, 16, v145
	v_and_b32_e32 v145, 0xffff0000, v145
	v_cvt_pk_bf16_f32 v127, v120, v121
	v_add_f32_e32 v118, v119, v118
	global_store_dwordx2 v[134:135], v[126:127], off offset:32
	v_add_f32_e32 v126, v128, v118
	v_pk_add_f32 v[118:119], v[124:125], v[144:145]
	v_pk_add_f32 v[120:121], v[122:123], v[146:147]
	v_cvt_pk_bf16_f32 v123, v118, v119
	v_cvt_pk_bf16_f32 v122, v120, v121
	v_mul_f32_e32 v121, v121, v121
	v_mul_f32_e32 v119, v119, v119
	v_lshlrev_b32_e32 v150, 16, v148
	v_and_b32_e32 v151, 0xffff0000, v148
	v_fmac_f32_e32 v121, v120, v120
	v_fmac_f32_e32 v119, v118, v118
	v_lshlrev_b32_e32 v148, 16, v149
	v_and_b32_e32 v149, 0xffff0000, v149
	v_add_f32_e32 v118, v121, v119
	v_pk_add_f32 v[114:115], v[114:115], v[150:151]
	v_add_f32_e32 v120, v126, v118
	v_pk_add_f32 v[116:117], v[116:117], v[148:149]
	v_cvt_pk_bf16_f32 v118, v114, v115
	v_mul_f32_e32 v115, v115, v115
	v_fmac_f32_e32 v115, v114, v114
	v_mul_f32_e32 v114, v117, v117
	v_cvt_pk_bf16_f32 v119, v116, v117
	v_fmac_f32_e32 v114, v116, v116
	v_and_b32_e32 v116, 64, v220
	v_add_f32_e32 v114, v115, v114
	v_xor_b32_e32 v115, 16, v220
	v_add_u32_e32 v117, 64, v116
	v_cmp_lt_i32_e32 vcc, v115, v117
	v_add_f32_e32 v114, v120, v114
	global_store_dwordx2 v[134:135], v[136:137], off
	v_cndmask_b32_e32 v115, v220, v115, vcc
	v_lshlrev_b32_e32 v116, 2, v115
	ds_bpermute_b32 v115, v116, v114
	global_store_dwordx2 v[134:135], v[122:123], off offset:256
	global_store_dwordx2 v[134:135], v[118:119], off offset:288
	s_waitcnt lgkmcnt(0)
	v_add_f32_e32 v114, v114, v115
	v_xor_b32_e32 v115, 32, v220
	v_cmp_lt_i32_e32 vcc, v115, v117
	s_nop 1
	v_cndmask_b32_e32 v115, v220, v115, vcc
	v_lshlrev_b32_e32 v117, 2, v115
	ds_bpermute_b32 v115, v117, v114
	s_and_saveexec_b64 s[14:15], s[36:37]
	s_cbranch_execz .LBB0_1776
	v_lshlrev_b64 v[118:119], 6, v[132:133]
	v_lshl_add_u64 v[118:119], s[0:1], 0, v[118:119]
	v_lshl_add_u64 v[118:119], s[48:49], 2, v[118:119]
	s_lshl_b32 s18, s74, 2
	v_lshl_add_u64 v[118:119], v[118:119], 0, s[18:19]
	s_waitcnt lgkmcnt(0)
	v_add_f32_e32 v114, v114, v115
	global_store_dword v[118:119], v114, off
